# conv-phase gate projection: k loop flattened with a rolling window of 10 k-steps of loads in flight
# speedup vs baseline: 1.0133x; 1.0008x over previous
.LBB0_821:
	v_add_co_u32_e32 v10, vcc, 0xdc40000, v8
	s_nop 1
	v_addc_co_u32_e32 v11, vcc, 0, v9, vcc
	v_add_co_u32_e32 v12, vcc, 0x8700000, v80
	s_nop 1
	v_addc_co_u32_e32 v13, vcc, 0, v81, vcc
	v_add_co_u32_e32 v14, vcc, 0x8708000, v80
	s_nop 1
	v_addc_co_u32_e32 v15, vcc, 0, v81, vcc
	global_load_dwordx4 v[16:19], v[10:11], off
	global_load_dwordx4 v[20:23], v[12:13], off
	global_load_dwordx4 v[24:27], v[14:15], off
	global_load_dwordx4 v[28:31], v[10:11], off offset:64
	global_load_dwordx4 v[32:35], v[12:13], off offset:64
	global_load_dwordx4 v[36:39], v[14:15], off offset:64
	global_load_dwordx4 v[40:43], v[10:11], off offset:128
	global_load_dwordx4 v[44:47], v[12:13], off offset:128
	global_load_dwordx4 v[48:51], v[14:15], off offset:128
	global_load_dwordx4 v[52:55], v[10:11], off offset:192
	global_load_dwordx4 v[56:59], v[12:13], off offset:192
	global_load_dwordx4 v[60:63], v[14:15], off offset:192
	global_load_dwordx4 v[88:91], v[10:11], off offset:256
	global_load_dwordx4 v[92:95], v[12:13], off offset:256
	global_load_dwordx4 v[96:99], v[14:15], off offset:256
	global_load_dwordx4 v[100:103], v[10:11], off offset:320
	global_load_dwordx4 v[116:119], v[12:13], off offset:320
	global_load_dwordx4 v[120:123], v[14:15], off offset:320
	global_load_dwordx4 v[124:127], v[10:11], off offset:384
	global_load_dwordx4 v[128:131], v[12:13], off offset:384
	global_load_dwordx4 v[132:135], v[14:15], off offset:384
	global_load_dwordx4 v[136:139], v[10:11], off offset:448
	global_load_dwordx4 v[140:143], v[12:13], off offset:448
	global_load_dwordx4 v[160:163], v[14:15], off offset:448
	global_load_dwordx4 v[164:167], v[10:11], off offset:512
	global_load_dwordx4 v[168:171], v[12:13], off offset:512
	global_load_dwordx4 v[172:175], v[14:15], off offset:512
	global_load_dwordx4 v[176:179], v[10:11], off offset:576
	global_load_dwordx4 v[180:183], v[12:13], off offset:576
	global_load_dwordx4 v[184:187], v[14:15], off offset:576
	s_waitcnt vmcnt(27)
	v_mfma_f32_16x16x32_bf16 v[0:3], v[16:19], v[20:23], v[0:3]
	v_mfma_f32_16x16x32_bf16 v[4:7], v[16:19], v[24:27], v[4:7]
	global_load_dwordx4 v[16:19], v[10:11], off offset:640
	global_load_dwordx4 v[20:23], v[12:13], off offset:640
	global_load_dwordx4 v[24:27], v[14:15], off offset:640
	s_waitcnt vmcnt(27)
	v_mfma_f32_16x16x32_bf16 v[0:3], v[28:31], v[32:35], v[0:3]
	v_mfma_f32_16x16x32_bf16 v[4:7], v[28:31], v[36:39], v[4:7]
	global_load_dwordx4 v[28:31], v[10:11], off offset:704
	global_load_dwordx4 v[32:35], v[12:13], off offset:704
	global_load_dwordx4 v[36:39], v[14:15], off offset:704
	s_waitcnt vmcnt(27)
	v_mfma_f32_16x16x32_bf16 v[0:3], v[40:43], v[44:47], v[0:3]
	v_mfma_f32_16x16x32_bf16 v[4:7], v[40:43], v[48:51], v[4:7]
	global_load_dwordx4 v[40:43], v[10:11], off offset:768
	global_load_dwordx4 v[44:47], v[12:13], off offset:768
	global_load_dwordx4 v[48:51], v[14:15], off offset:768
	s_waitcnt vmcnt(27)
	v_mfma_f32_16x16x32_bf16 v[0:3], v[52:55], v[56:59], v[0:3]
	v_mfma_f32_16x16x32_bf16 v[4:7], v[52:55], v[60:63], v[4:7]
	global_load_dwordx4 v[52:55], v[10:11], off offset:832
	global_load_dwordx4 v[56:59], v[12:13], off offset:832
	global_load_dwordx4 v[60:63], v[14:15], off offset:832
	s_waitcnt vmcnt(27)
	v_mfma_f32_16x16x32_bf16 v[0:3], v[88:91], v[92:95], v[0:3]
	v_mfma_f32_16x16x32_bf16 v[4:7], v[88:91], v[96:99], v[4:7]
	global_load_dwordx4 v[88:91], v[10:11], off offset:896
	global_load_dwordx4 v[92:95], v[12:13], off offset:896
	global_load_dwordx4 v[96:99], v[14:15], off offset:896
	s_waitcnt vmcnt(27)
	v_mfma_f32_16x16x32_bf16 v[0:3], v[100:103], v[116:119], v[0:3]
	v_mfma_f32_16x16x32_bf16 v[4:7], v[100:103], v[120:123], v[4:7]
	global_load_dwordx4 v[100:103], v[10:11], off offset:960
	global_load_dwordx4 v[116:119], v[12:13], off offset:960
	global_load_dwordx4 v[120:123], v[14:15], off offset:960
	s_waitcnt vmcnt(27)
	v_mfma_f32_16x16x32_bf16 v[0:3], v[124:127], v[128:131], v[0:3]
	v_mfma_f32_16x16x32_bf16 v[4:7], v[124:127], v[132:135], v[4:7]
	global_load_dwordx4 v[124:127], v[10:11], off offset:1024
	global_load_dwordx4 v[128:131], v[12:13], off offset:1024
	global_load_dwordx4 v[132:135], v[14:15], off offset:1024
	s_waitcnt vmcnt(27)
	v_mfma_f32_16x16x32_bf16 v[0:3], v[136:139], v[140:143], v[0:3]
	v_mfma_f32_16x16x32_bf16 v[4:7], v[136:139], v[160:163], v[4:7]
	global_load_dwordx4 v[136:139], v[10:11], off offset:1088
	global_load_dwordx4 v[140:143], v[12:13], off offset:1088
	global_load_dwordx4 v[160:163], v[14:15], off offset:1088
	s_waitcnt vmcnt(27)
	v_mfma_f32_16x16x32_bf16 v[0:3], v[164:167], v[168:171], v[0:3]
	v_mfma_f32_16x16x32_bf16 v[4:7], v[164:167], v[172:175], v[4:7]
	global_load_dwordx4 v[164:167], v[10:11], off offset:1152
	global_load_dwordx4 v[168:171], v[12:13], off offset:1152
	global_load_dwordx4 v[172:175], v[14:15], off offset:1152
	s_waitcnt vmcnt(27)
	v_mfma_f32_16x16x32_bf16 v[0:3], v[176:179], v[180:183], v[0:3]
	v_mfma_f32_16x16x32_bf16 v[4:7], v[176:179], v[184:187], v[4:7]
	global_load_dwordx4 v[176:179], v[10:11], off offset:1216
	global_load_dwordx4 v[180:183], v[12:13], off offset:1216
	global_load_dwordx4 v[184:187], v[14:15], off offset:1216
	s_waitcnt vmcnt(27)
	v_mfma_f32_16x16x32_bf16 v[0:3], v[16:19], v[20:23], v[0:3]
	v_mfma_f32_16x16x32_bf16 v[4:7], v[16:19], v[24:27], v[4:7]
	global_load_dwordx4 v[16:19], v[10:11], off offset:1280
	global_load_dwordx4 v[20:23], v[12:13], off offset:1280
	global_load_dwordx4 v[24:27], v[14:15], off offset:1280
	s_waitcnt vmcnt(27)
	v_mfma_f32_16x16x32_bf16 v[0:3], v[28:31], v[32:35], v[0:3]
	v_mfma_f32_16x16x32_bf16 v[4:7], v[28:31], v[36:39], v[4:7]
	global_load_dwordx4 v[28:31], v[10:11], off offset:1344
	global_load_dwordx4 v[32:35], v[12:13], off offset:1344
	global_load_dwordx4 v[36:39], v[14:15], off offset:1344
	s_waitcnt vmcnt(27)
	v_mfma_f32_16x16x32_bf16 v[0:3], v[40:43], v[44:47], v[0:3]
	v_mfma_f32_16x16x32_bf16 v[4:7], v[40:43], v[48:51], v[4:7]
	global_load_dwordx4 v[40:43], v[10:11], off offset:1408
	global_load_dwordx4 v[44:47], v[12:13], off offset:1408
	global_load_dwordx4 v[48:51], v[14:15], off offset:1408
	s_waitcnt vmcnt(27)
	v_mfma_f32_16x16x32_bf16 v[0:3], v[52:55], v[56:59], v[0:3]
	v_mfma_f32_16x16x32_bf16 v[4:7], v[52:55], v[60:63], v[4:7]
	global_load_dwordx4 v[52:55], v[10:11], off offset:1472
	global_load_dwordx4 v[56:59], v[12:13], off offset:1472
	global_load_dwordx4 v[60:63], v[14:15], off offset:1472
	s_waitcnt vmcnt(27)
	v_mfma_f32_16x16x32_bf16 v[0:3], v[88:91], v[92:95], v[0:3]
	v_mfma_f32_16x16x32_bf16 v[4:7], v[88:91], v[96:99], v[4:7]
	global_load_dwordx4 v[88:91], v[10:11], off offset:1536
	global_load_dwordx4 v[92:95], v[12:13], off offset:1536
	global_load_dwordx4 v[96:99], v[14:15], off offset:1536
	s_waitcnt vmcnt(27)
	v_mfma_f32_16x16x32_bf16 v[0:3], v[100:103], v[116:119], v[0:3]
	v_mfma_f32_16x16x32_bf16 v[4:7], v[100:103], v[120:123], v[4:7]
	global_load_dwordx4 v[100:103], v[10:11], off offset:1600
	global_load_dwordx4 v[116:119], v[12:13], off offset:1600
	global_load_dwordx4 v[120:123], v[14:15], off offset:1600
	s_waitcnt vmcnt(27)
	v_mfma_f32_16x16x32_bf16 v[0:3], v[124:127], v[128:131], v[0:3]
	v_mfma_f32_16x16x32_bf16 v[4:7], v[124:127], v[132:135], v[4:7]
	global_load_dwordx4 v[124:127], v[10:11], off offset:1664
	global_load_dwordx4 v[128:131], v[12:13], off offset:1664
	global_load_dwordx4 v[132:135], v[14:15], off offset:1664
	s_waitcnt vmcnt(27)
	v_mfma_f32_16x16x32_bf16 v[0:3], v[136:139], v[140:143], v[0:3]
	v_mfma_f32_16x16x32_bf16 v[4:7], v[136:139], v[160:163], v[4:7]
	global_load_dwordx4 v[136:139], v[10:11], off offset:1728
	global_load_dwordx4 v[140:143], v[12:13], off offset:1728
	global_load_dwordx4 v[160:163], v[14:15], off offset:1728
	s_waitcnt vmcnt(27)
	v_mfma_f32_16x16x32_bf16 v[0:3], v[164:167], v[168:171], v[0:3]
	v_mfma_f32_16x16x32_bf16 v[4:7], v[164:167], v[172:175], v[4:7]
	global_load_dwordx4 v[164:167], v[10:11], off offset:1792
	global_load_dwordx4 v[168:171], v[12:13], off offset:1792
	global_load_dwordx4 v[172:175], v[14:15], off offset:1792
	s_waitcnt vmcnt(27)
	v_mfma_f32_16x16x32_bf16 v[0:3], v[176:179], v[180:183], v[0:3]
	v_mfma_f32_16x16x32_bf16 v[4:7], v[176:179], v[184:187], v[4:7]
	global_load_dwordx4 v[176:179], v[10:11], off offset:1856
	global_load_dwordx4 v[180:183], v[12:13], off offset:1856
	global_load_dwordx4 v[184:187], v[14:15], off offset:1856
	s_waitcnt vmcnt(27)
	v_mfma_f32_16x16x32_bf16 v[0:3], v[16:19], v[20:23], v[0:3]
	v_mfma_f32_16x16x32_bf16 v[4:7], v[16:19], v[24:27], v[4:7]
	global_load_dwordx4 v[16:19], v[10:11], off offset:1920
	global_load_dwordx4 v[20:23], v[12:13], off offset:1920
	global_load_dwordx4 v[24:27], v[14:15], off offset:1920
	s_waitcnt vmcnt(27)
	v_mfma_f32_16x16x32_bf16 v[0:3], v[28:31], v[32:35], v[0:3]
	v_mfma_f32_16x16x32_bf16 v[4:7], v[28:31], v[36:39], v[4:7]
	global_load_dwordx4 v[28:31], v[10:11], off offset:1984
	global_load_dwordx4 v[32:35], v[12:13], off offset:1984
	global_load_dwordx4 v[36:39], v[14:15], off offset:1984
	s_waitcnt vmcnt(27)
	v_mfma_f32_16x16x32_bf16 v[0:3], v[40:43], v[44:47], v[0:3]
	v_mfma_f32_16x16x32_bf16 v[4:7], v[40:43], v[48:51], v[4:7]
	s_waitcnt vmcnt(24)
	v_mfma_f32_16x16x32_bf16 v[0:3], v[52:55], v[56:59], v[0:3]
	v_mfma_f32_16x16x32_bf16 v[4:7], v[52:55], v[60:63], v[4:7]
	s_waitcnt vmcnt(21)
	v_mfma_f32_16x16x32_bf16 v[0:3], v[88:91], v[92:95], v[0:3]
	v_mfma_f32_16x16x32_bf16 v[4:7], v[88:91], v[96:99], v[4:7]
	s_waitcnt vmcnt(18)
	v_mfma_f32_16x16x32_bf16 v[0:3], v[100:103], v[116:119], v[0:3]
	v_mfma_f32_16x16x32_bf16 v[4:7], v[100:103], v[120:123], v[4:7]
	s_waitcnt vmcnt(15)
	v_mfma_f32_16x16x32_bf16 v[0:3], v[124:127], v[128:131], v[0:3]
	v_mfma_f32_16x16x32_bf16 v[4:7], v[124:127], v[132:135], v[4:7]
	s_waitcnt vmcnt(12)
	v_mfma_f32_16x16x32_bf16 v[0:3], v[136:139], v[140:143], v[0:3]
	v_mfma_f32_16x16x32_bf16 v[4:7], v[136:139], v[160:163], v[4:7]
	s_waitcnt vmcnt(9)
	v_mfma_f32_16x16x32_bf16 v[0:3], v[164:167], v[168:171], v[0:3]
	v_mfma_f32_16x16x32_bf16 v[4:7], v[164:167], v[172:175], v[4:7]
	s_waitcnt vmcnt(6)
	v_mfma_f32_16x16x32_bf16 v[0:3], v[176:179], v[180:183], v[0:3]
	v_mfma_f32_16x16x32_bf16 v[4:7], v[176:179], v[184:187], v[4:7]
	s_waitcnt vmcnt(3)
	v_mfma_f32_16x16x32_bf16 v[0:3], v[16:19], v[20:23], v[0:3]
	v_mfma_f32_16x16x32_bf16 v[4:7], v[16:19], v[24:27], v[4:7]
	s_waitcnt vmcnt(0)
	v_mfma_f32_16x16x32_bf16 v[0:3], v[28:31], v[32:35], v[0:3]
	v_mfma_f32_16x16x32_bf16 v[4:7], v[28:31], v[36:39], v[4:7]
	global_load_dword v13, v[74:75], off
	v_lshlrev_b32_e32 v14, 4, v86
	v_or_b32_e32 v12, v14, v154
	v_add_u32_e32 v66, 0xfffe8000, v12
	v_lshl_add_u64 v[10:11], v[66:67], 2, s[34:35]
	global_load_dword v16, v[10:11], off
	v_add_u32_e32 v10, 0xfffe7000, v14
	v_ashrrev_i32_e32 v10, 10, v10
	v_add_u32_e32 v10, 11, v10
	v_cmp_lt_u32_e32 vcc, s52, v86
	v_mov_b64_e32 v[8:9], s[22:23]
	v_mov_b32_e32 v83, v67
	v_cndmask_b32_e32 v10, 10, v10, vcc
	v_mad_u64_u32 v[8:9], s[0:1], v10, s53, v[8:9]
	v_lshl_add_u64 v[8:9], v[8:9], 0, s[38:39]
	v_mov_b32_e32 v85, v67
	v_lshl_add_u64 v[10:11], v[8:9], 0, v[82:83]
	v_lshl_add_u64 v[14:15], v[8:9], 0, v[84:85]
	global_load_dword v9, v[10:11], off
	s_nop 0
	global_load_dword v10, v[14:15], off
	global_load_dword v11, v[72:73], off
	s_waitcnt vmcnt(4)
	v_mul_f32_e32 v8, 0x3fb8aa3b, v13
	v_rndne_f32_e32 v14, v8
	v_fma_f32 v15, v13, s54, -v8
	v_sub_f32_e32 v8, v8, v14
	v_fmac_f32_e32 v15, 0x32a5705f, v13
	v_add_f32_e32 v8, v8, v15
	v_cvt_i32_f32_e32 v17, v14
	v_exp_f32_e32 v8, v8
	s_waitcnt vmcnt(3)
	v_fmamk_f32 v16, v16, 0x3a800000, v65
	v_cmp_gt_f32_e32 vcc, s49, v16
	v_cmp_ngt_f32_e64 s[10:11], s55, v13
	v_ldexp_f32 v8, v8, v17
	v_mul_f32_e32 v17, 0x4b800000, v16
	v_cndmask_b32_e32 v16, v16, v17, vcc
	v_rsq_f32_e32 v16, v16
	v_cndmask_b32_e64 v8, 0, v8, s[10:11]
	v_cmp_nlt_f32_e64 s[10:11], s56, v13
	v_lshlrev_b64 v[14:15], 7, v[66:67]
	v_mul_f32_e32 v13, 0x45800000, v16
	v_cndmask_b32_e32 v13, v16, v13, vcc
	s_waitcnt vmcnt(2)
	v_fma_f32 v0, v0, v13, v9
	s_waitcnt vmcnt(1)
	v_fma_f32 v4, v4, v13, v10
	v_mul_f32_e32 v13, 0xbfb8aa3b, v0
	s_waitcnt vmcnt(0)
	v_add_f32_e32 v4, v11, v4
	v_fma_f32 v16, v0, s48, -v13
	v_rndne_f32_e32 v17, v13
	v_mul_f32_e64 v19, |v4|, s48
	v_fmac_f32_e32 v16, 0xb2a5705f, v0
	v_sub_f32_e32 v13, v13, v17
	v_fma_f32 v20, |v4|, s48, -v19
	v_rndne_f32_e32 v21, v19
	v_add_f32_e32 v13, v13, v16
	v_cvt_i32_f32_e32 v17, v17
	v_fma_f32 v16, |v4|, s58, v20
	v_sub_f32_e32 v19, v19, v21
	v_exp_f32_e32 v13, v13
	v_add_f32_e32 v16, v19, v16
	v_cvt_i32_f32_e32 v20, v21
	v_exp_f32_e32 v16, v16
	v_ldexp_f32 v13, v13, v17
	v_cmp_nlt_f32_e32 vcc, s59, v0
	v_max_f32_e32 v18, 0, v4
	v_ldexp_f32 v16, v16, v20
	v_cndmask_b32_e32 v13, 0, v13, vcc
	v_cmp_ngt_f32_e32 vcc, s60, v0
	v_cndmask_b32_e64 v8, v112, v8, s[10:11]
	v_lshl_add_u64 v[14:15], v[68:69], 0, v[14:15]
	v_cndmask_b32_e32 v0, v112, v13, vcc
	v_cmp_ngt_f32_e64 vcc, |v4|, s59
	v_add_f32_e32 v0, 1.0, v0
	v_add_u32_e32 v66, 0xfffe8001, v12
	v_cndmask_b32_e32 v13, 0, v16, vcc
	v_cmp_nlt_f32_e64 vcc, |v4|, s60
	s_nop 1
	v_cndmask_b32_e32 v4, v112, v13, vcc
	v_div_scale_f32 v13, s[0:1], v0, v0, 1.0
	v_add_f32_e32 v20, 1.0, v4
	v_rcp_f32_e32 v21, v13
	v_add_f32_e32 v22, -1.0, v20
	v_frexp_mant_f32_e32 v23, v20
	v_cvt_f64_f32_e32 v[16:17], v20
	v_sub_f32_e32 v24, v22, v20
	v_frexp_exp_i32_f64_e32 v16, v[16:17]
	v_cmp_gt_f32_e64 s[10:11], s61, v23
	v_sub_f32_e32 v22, v4, v22
	v_add_f32_e32 v17, 1.0, v24
	v_subbrev_co_u32_e64 v16, s[10:11], 0, v16, s[10:11]
	v_add_f32_e32 v17, v22, v17
	v_sub_u32_e32 v22, 0, v16
	v_fma_f32 v23, -v13, v21, 1.0
	v_ldexp_f32 v20, v20, v22
	v_div_scale_f32 v19, vcc, 1.0, v0, 1.0
	v_ldexp_f32 v17, v17, v22
	v_fmac_f32_e32 v21, v23, v21
	v_add_f32_e32 v22, -1.0, v20
	v_add_f32_e32 v23, 1.0, v20
	v_mul_f32_e32 v24, v19, v21
	v_add_f32_e32 v25, 1.0, v22
	v_add_f32_e32 v26, -1.0, v23
	v_fma_f32 v27, -v13, v24, v19
	v_sub_f32_e32 v25, v20, v25
	v_sub_f32_e32 v20, v20, v26
	v_fmac_f32_e32 v24, v27, v21
	v_add_f32_e32 v25, v17, v25
	v_add_f32_e32 v17, v17, v20
	v_fma_f32 v13, -v13, v24, v19
	v_add_f32_e32 v19, v22, v25
	v_add_f32_e32 v20, v23, v17
	v_div_fmas_f32 v13, v13, v21, v24
	v_sub_f32_e32 v21, v22, v19
	v_sub_f32_e32 v22, v23, v20
	v_rcp_f32_e32 v23, v20
	v_div_fixup_f32 v0, v13, v0, 1.0
	global_store_dword v[14:15], v0, off
	v_add_f32_e32 v13, v25, v21
	v_mul_f32_e32 v0, v19, v23
	v_mul_f32_e32 v21, v20, v0
	v_add_f32_e32 v17, v17, v22
	v_fma_f32 v22, v0, v20, -v21
	v_fmac_f32_e32 v22, v0, v17
	v_add_f32_e32 v24, v21, v22
	v_sub_f32_e32 v25, v19, v24
	v_sub_f32_e32 v19, v19, v25
	v_sub_f32_e32 v21, v24, v21
	v_sub_f32_e32 v19, v19, v24
	v_sub_f32_e32 v21, v21, v22
	v_add_f32_e32 v13, v13, v19
	v_add_f32_e32 v13, v21, v13
	v_add_f32_e32 v19, v25, v13
	v_mul_f32_e32 v21, v23, v19
	v_mul_f32_e32 v24, v20, v21
	v_fma_f32 v20, v21, v20, -v24
	v_fmac_f32_e32 v20, v21, v17
	v_sub_f32_e32 v22, v25, v19
	v_add_f32_e32 v17, v24, v20
	v_add_f32_e32 v13, v13, v22
	v_sub_f32_e32 v22, v17, v24
	v_sub_f32_e32 v24, v19, v17
	v_sub_f32_e32 v19, v19, v24
	v_sub_f32_e32 v17, v19, v17
	v_add_f32_e32 v13, v13, v17
	v_sub_f32_e32 v17, v22, v20
	v_cvt_f32_i32_e32 v16, v16
	v_add_f32_e32 v13, v17, v13
	v_add_f32_e32 v17, v0, v21
	v_add_f32_e32 v13, v24, v13
	v_sub_f32_e32 v0, v17, v0
	v_mul_f32_e32 v13, v23, v13
	v_sub_f32_e32 v0, v21, v0
	v_add_f32_e32 v0, v0, v13
	v_mul_f32_e32 v21, 0x3f317218, v16
	v_add_f32_e32 v13, v17, v0
	v_fma_f32 v22, v16, s62, -v21
	v_mul_f32_e32 v19, v13, v13
	v_fmac_f32_e32 v22, 0xb102e308, v16
	v_sub_f32_e32 v16, v13, v17
	v_fmamk_f32 v20, v19, 0x3e9b6dac, v71
	v_sub_f32_e32 v0, v0, v16
	v_add_f32_e32 v16, v21, v22
	v_fmaak_f32 v20, v19, v20, 0x3f2aaada
	v_sub_f32_e32 v17, v16, v21
	v_ldexp_f32 v21, v13, 1
	v_mul_f32_e32 v13, v13, v19
	v_mul_f32_e32 v13, v13, v20
	v_add_f32_e32 v19, v21, v13
	v_sub_f32_e32 v20, v19, v21
	v_ldexp_f32 v0, v0, 1
	v_sub_f32_e32 v13, v13, v20
	v_add_f32_e32 v0, v0, v13
	v_add_f32_e32 v13, v19, v0
	v_sub_f32_e32 v19, v13, v19
	v_sub_f32_e32 v0, v0, v19
	v_add_f32_e32 v19, v16, v13
	v_sub_f32_e32 v20, v19, v16
	v_sub_f32_e32 v21, v19, v20
	v_sub_f32_e32 v17, v22, v17
	v_sub_f32_e32 v16, v16, v21
	v_sub_f32_e32 v13, v13, v20
	v_add_f32_e32 v13, v13, v16
	v_add_f32_e32 v16, v17, v0
	v_sub_f32_e32 v20, v16, v17
	v_sub_f32_e32 v21, v16, v20
	v_add_f32_e32 v13, v16, v13
	v_sub_f32_e32 v17, v17, v21
	v_sub_f32_e32 v0, v0, v20
	v_add_f32_e32 v16, v19, v13
	v_add_f32_e32 v0, v0, v17
	v_sub_f32_e32 v17, v16, v19
	v_sub_f32_e32 v13, v13, v17
	v_add_f32_e32 v0, v0, v13
	v_add_f32_e32 v0, v16, v0
	v_cmp_neq_f32_e32 vcc, s57, v4
	s_nop 1
	v_cndmask_b32_e32 v0, v112, v0, vcc
	v_cmp_lt_f32_e64 vcc, |v4|, s63
	s_nop 1
	v_cndmask_b32_e32 v0, v0, v4, vcc
	v_add_f32_e32 v0, v18, v0
	v_mul_f32_e64 v0, v0, -v8
	global_store_dword v[14:15], v0, off offset:64
	v_lshl_add_u64 v[14:15], v[66:67], 2, s[34:35]
	global_load_dword v0, v[14:15], off
	v_lshlrev_b64 v[14:15], 7, v[66:67]
	v_lshl_add_u64 v[14:15], v[68:69], 0, v[14:15]
	v_add_u32_e32 v66, 0xfffe8002, v12
	s_waitcnt vmcnt(0)
	v_fmamk_f32 v0, v0, 0x3a800000, v65
	v_mul_f32_e32 v4, 0x4b800000, v0
	v_cmp_gt_f32_e32 vcc, s49, v0
	s_nop 1
	v_cndmask_b32_e32 v0, v0, v4, vcc
	v_rsq_f32_e32 v0, v0
	s_nop 0
	v_mul_f32_e32 v4, 0x45800000, v0
	v_cndmask_b32_e32 v0, v0, v4, vcc
	v_fma_f32 v1, v1, v0, v9
	v_fma_f32 v0, v5, v0, v10
	v_mul_f32_e32 v4, 0xbfb8aa3b, v1
	v_add_f32_e32 v0, v11, v0
	v_fma_f32 v5, v1, s48, -v4
	v_rndne_f32_e32 v13, v4
	v_mul_f32_e64 v17, |v0|, s48
	v_fmac_f32_e32 v5, 0xb2a5705f, v1
	v_sub_f32_e32 v4, v4, v13
	v_fma_f32 v18, |v0|, s48, -v17
	v_rndne_f32_e32 v19, v17
	v_add_f32_e32 v4, v4, v5
	v_cvt_i32_f32_e32 v13, v13
	v_fma_f32 v5, |v0|, s58, v18
	v_sub_f32_e32 v17, v17, v19
	v_exp_f32_e32 v4, v4
	v_add_f32_e32 v5, v17, v5
	v_cvt_i32_f32_e32 v18, v19
	v_exp_f32_e32 v5, v5
	v_ldexp_f32 v4, v4, v13
	v_cmp_nlt_f32_e32 vcc, s59, v1
	v_max_f32_e32 v16, 0, v0
	v_ldexp_f32 v5, v5, v18
	v_cndmask_b32_e32 v4, 0, v4, vcc
	v_cmp_ngt_f32_e32 vcc, s60, v1
	s_nop 1
	v_cndmask_b32_e32 v1, v112, v4, vcc
	v_cmp_ngt_f32_e64 vcc, |v0|, s59
	s_nop 1
	v_cndmask_b32_e32 v4, 0, v5, vcc
	v_cmp_nlt_f32_e64 vcc, |v0|, s60
	v_add_f32_e32 v5, 1.0, v1
	v_div_scale_f32 v13, s[0:1], v5, v5, 1.0
	v_cndmask_b32_e32 v4, v112, v4, vcc
	v_add_f32_e32 v18, 1.0, v4
	v_rcp_f32_e32 v19, v13
	v_add_f32_e32 v20, -1.0, v18
	v_frexp_mant_f32_e32 v21, v18
	v_cvt_f64_f32_e32 v[0:1], v18
	v_sub_f32_e32 v22, v20, v18
	v_frexp_exp_i32_f64_e32 v0, v[0:1]
	v_cmp_gt_f32_e64 s[10:11], s61, v21
	v_sub_f32_e32 v20, v4, v20
	v_add_f32_e32 v1, 1.0, v22
	v_subbrev_co_u32_e64 v0, s[10:11], 0, v0, s[10:11]
	v_add_f32_e32 v1, v20, v1
	v_sub_u32_e32 v20, 0, v0
	v_fma_f32 v21, -v13, v19, 1.0
	v_ldexp_f32 v18, v18, v20
	v_div_scale_f32 v17, vcc, 1.0, v5, 1.0
	v_ldexp_f32 v1, v1, v20
	v_fmac_f32_e32 v19, v21, v19
	v_add_f32_e32 v20, -1.0, v18
	v_add_f32_e32 v21, 1.0, v18
	v_mul_f32_e32 v22, v17, v19
	v_add_f32_e32 v23, 1.0, v20
	v_add_f32_e32 v24, -1.0, v21
	v_fma_f32 v25, -v13, v22, v17
	v_sub_f32_e32 v23, v18, v23
	v_sub_f32_e32 v18, v18, v24
	v_fmac_f32_e32 v22, v25, v19
	v_add_f32_e32 v23, v1, v23
	v_add_f32_e32 v1, v1, v18
	v_fma_f32 v13, -v13, v22, v17
	v_add_f32_e32 v17, v20, v23
	v_add_f32_e32 v18, v21, v1
	v_div_fmas_f32 v13, v13, v19, v22
	v_sub_f32_e32 v19, v20, v17
	v_sub_f32_e32 v20, v21, v18
	v_rcp_f32_e32 v21, v18
	v_div_fixup_f32 v5, v13, v5, 1.0
	global_store_dword v[14:15], v5, off
	v_add_f32_e32 v13, v23, v19
	v_mul_f32_e32 v5, v17, v21
	v_mul_f32_e32 v19, v18, v5
	v_add_f32_e32 v1, v1, v20
	v_fma_f32 v20, v5, v18, -v19
	v_fmac_f32_e32 v20, v5, v1
	v_add_f32_e32 v22, v19, v20
	v_sub_f32_e32 v23, v17, v22
	v_sub_f32_e32 v17, v17, v23
	v_sub_f32_e32 v19, v22, v19
	v_sub_f32_e32 v17, v17, v22
	v_sub_f32_e32 v19, v19, v20
	v_add_f32_e32 v13, v13, v17
	v_add_f32_e32 v13, v19, v13
	v_add_f32_e32 v17, v23, v13
	v_mul_f32_e32 v19, v21, v17
	v_mul_f32_e32 v20, v18, v19
	v_fma_f32 v18, v19, v18, -v20
	v_fmac_f32_e32 v18, v19, v1
	v_sub_f32_e32 v1, v23, v17
	v_add_f32_e32 v1, v13, v1
	v_add_f32_e32 v13, v20, v18
	v_sub_f32_e32 v22, v17, v13
	v_sub_f32_e32 v17, v17, v22
	v_sub_f32_e32 v20, v13, v20
	v_sub_f32_e32 v13, v17, v13
	v_add_f32_e32 v1, v1, v13
	v_sub_f32_e32 v13, v20, v18
	v_cvt_f32_i32_e32 v0, v0
	v_add_f32_e32 v1, v13, v1
	v_add_f32_e32 v13, v5, v19
	v_add_f32_e32 v1, v22, v1
	v_sub_f32_e32 v5, v13, v5
	v_mul_f32_e32 v1, v21, v1
	v_sub_f32_e32 v5, v19, v5
	v_add_f32_e32 v1, v5, v1
	v_mul_f32_e32 v19, 0x3f317218, v0
	v_add_f32_e32 v5, v13, v1
	v_fma_f32 v20, v0, s62, -v19
	v_mul_f32_e32 v17, v5, v5
	v_fmac_f32_e32 v20, 0xb102e308, v0
	v_sub_f32_e32 v0, v5, v13
	v_fmamk_f32 v18, v17, 0x3e9b6dac, v71
	v_sub_f32_e32 v0, v1, v0
	v_add_f32_e32 v1, v19, v20
	v_fmaak_f32 v18, v17, v18, 0x3f2aaada
	v_sub_f32_e32 v13, v1, v19
	v_ldexp_f32 v19, v5, 1
	v_mul_f32_e32 v5, v5, v17
	v_mul_f32_e32 v5, v5, v18
	v_add_f32_e32 v17, v19, v5
	v_sub_f32_e32 v18, v17, v19
	v_ldexp_f32 v0, v0, 1
	v_sub_f32_e32 v5, v5, v18
	v_add_f32_e32 v0, v0, v5
	v_add_f32_e32 v5, v17, v0
	v_sub_f32_e32 v17, v5, v17
	v_sub_f32_e32 v0, v0, v17
	v_add_f32_e32 v17, v1, v5
	v_sub_f32_e32 v18, v17, v1
	v_sub_f32_e32 v19, v17, v18
	v_sub_f32_e32 v13, v20, v13
	v_sub_f32_e32 v1, v1, v19
	v_sub_f32_e32 v5, v5, v18
	v_add_f32_e32 v1, v5, v1
	v_add_f32_e32 v5, v13, v0
	v_sub_f32_e32 v18, v5, v13
	v_sub_f32_e32 v19, v5, v18
	v_add_f32_e32 v1, v5, v1
	v_sub_f32_e32 v13, v13, v19
	v_sub_f32_e32 v0, v0, v18
	v_add_f32_e32 v5, v17, v1
	v_add_f32_e32 v0, v0, v13
	v_sub_f32_e32 v13, v5, v17
	v_sub_f32_e32 v1, v1, v13
	v_add_f32_e32 v0, v0, v1
	v_add_f32_e32 v0, v5, v0
	v_cmp_neq_f32_e32 vcc, s57, v4
	s_nop 1
	v_cndmask_b32_e32 v0, v112, v0, vcc
	v_cmp_lt_f32_e64 vcc, |v4|, s63
	s_nop 1
	v_cndmask_b32_e32 v0, v0, v4, vcc
	v_add_f32_e32 v0, v16, v0
	v_mul_f32_e64 v0, v0, -v8
	global_store_dword v[14:15], v0, off offset:64
	v_lshl_add_u64 v[0:1], v[66:67], 2, s[34:35]
	global_load_dword v0, v[0:1], off
	s_waitcnt vmcnt(0)
	v_fmamk_f32 v0, v0, 0x3a800000, v65
	v_mul_f32_e32 v1, 0x4b800000, v0
	v_cmp_gt_f32_e32 vcc, s49, v0
	s_nop 1
	v_cndmask_b32_e32 v0, v0, v1, vcc
	v_rsq_f32_e32 v4, v0
	v_lshlrev_b64 v[0:1], 7, v[66:67]
	v_lshl_add_u64 v[0:1], v[68:69], 0, v[0:1]
	v_add_u32_e32 v66, 0xfffe8003, v12
	v_mul_f32_e32 v5, 0x45800000, v4
	v_cndmask_b32_e32 v4, v4, v5, vcc
	v_fma_f32 v2, v2, v4, v9
	v_fma_f32 v4, v6, v4, v10
	v_mul_f32_e32 v5, 0xbfb8aa3b, v2
	v_add_f32_e32 v4, v11, v4
	v_fma_f32 v6, v2, s48, -v5
	v_rndne_f32_e32 v13, v5
	v_mul_f32_e64 v15, |v4|, s48
	v_fmac_f32_e32 v6, 0xb2a5705f, v2
	v_sub_f32_e32 v5, v5, v13
	v_fma_f32 v16, |v4|, s48, -v15
	v_rndne_f32_e32 v17, v15
	v_add_f32_e32 v5, v5, v6
	v_cvt_i32_f32_e32 v13, v13
	v_fma_f32 v6, |v4|, s58, v16
	v_sub_f32_e32 v15, v15, v17
	v_exp_f32_e32 v5, v5
	v_add_f32_e32 v6, v15, v6
	v_cvt_i32_f32_e32 v16, v17
	v_exp_f32_e32 v6, v6
	v_ldexp_f32 v5, v5, v13
	v_cmp_nlt_f32_e32 vcc, s59, v2
	v_max_f32_e32 v14, 0, v4
	v_ldexp_f32 v6, v6, v16
	v_cndmask_b32_e32 v5, 0, v5, vcc
	v_cmp_ngt_f32_e32 vcc, s60, v2
	s_nop 1
	v_cndmask_b32_e32 v2, v112, v5, vcc
	v_cmp_ngt_f32_e64 vcc, |v4|, s59
	v_add_f32_e32 v2, 1.0, v2
	v_div_scale_f32 v13, s[0:1], v2, v2, 1.0
	v_cndmask_b32_e32 v5, 0, v6, vcc
	v_cmp_nlt_f32_e64 vcc, |v4|, s60
	v_rcp_f32_e32 v17, v13
	s_nop 0
	v_cndmask_b32_e32 v6, v112, v5, vcc
	v_add_f32_e32 v16, 1.0, v6
	v_add_f32_e32 v18, -1.0, v16
	v_frexp_mant_f32_e32 v19, v16
	v_cvt_f64_f32_e32 v[4:5], v16
	v_sub_f32_e32 v20, v18, v16
	v_frexp_exp_i32_f64_e32 v4, v[4:5]
	v_cmp_gt_f32_e64 s[10:11], s61, v19
	v_sub_f32_e32 v18, v6, v18
	v_add_f32_e32 v5, 1.0, v20
	v_subbrev_co_u32_e64 v4, s[10:11], 0, v4, s[10:11]
	v_add_f32_e32 v5, v18, v5
	v_sub_u32_e32 v18, 0, v4
	v_fma_f32 v19, -v13, v17, 1.0
	v_ldexp_f32 v16, v16, v18
	v_div_scale_f32 v15, vcc, 1.0, v2, 1.0
	v_ldexp_f32 v5, v5, v18
	v_fmac_f32_e32 v17, v19, v17
	v_add_f32_e32 v18, -1.0, v16
	v_add_f32_e32 v19, 1.0, v16
	v_mul_f32_e32 v20, v15, v17
	v_add_f32_e32 v21, 1.0, v18
	v_add_f32_e32 v22, -1.0, v19
	v_fma_f32 v23, -v13, v20, v15
	v_sub_f32_e32 v21, v16, v21
	v_sub_f32_e32 v16, v16, v22
	v_fmac_f32_e32 v20, v23, v17
	v_add_f32_e32 v21, v5, v21
	v_add_f32_e32 v5, v5, v16
	v_fma_f32 v13, -v13, v20, v15
	v_add_f32_e32 v15, v18, v21
	v_add_f32_e32 v16, v19, v5
	v_div_fmas_f32 v13, v13, v17, v20
	v_sub_f32_e32 v17, v18, v15
	v_rcp_f32_e32 v18, v16
	v_div_fixup_f32 v2, v13, v2, 1.0
	global_store_dword v[0:1], v2, off
	v_sub_f32_e32 v2, v19, v16
	v_add_f32_e32 v2, v5, v2
	v_mul_f32_e32 v5, v15, v18
	v_add_f32_e32 v13, v21, v17
	v_mul_f32_e32 v17, v16, v5
	v_fma_f32 v19, v5, v16, -v17
	v_fmac_f32_e32 v19, v5, v2
	v_add_f32_e32 v20, v17, v19
	v_sub_f32_e32 v21, v15, v20
	v_sub_f32_e32 v15, v15, v21
	v_sub_f32_e32 v17, v20, v17
	v_sub_f32_e32 v15, v15, v20
	v_add_f32_e32 v13, v13, v15
	v_sub_f32_e32 v15, v17, v19
	v_add_f32_e32 v13, v15, v13
	v_add_f32_e32 v15, v21, v13
	v_mul_f32_e32 v17, v18, v15
	v_mul_f32_e32 v19, v16, v17
	v_fma_f32 v16, v17, v16, -v19
	v_fmac_f32_e32 v16, v17, v2
	v_sub_f32_e32 v2, v21, v15
	v_add_f32_e32 v2, v13, v2
	v_add_f32_e32 v13, v19, v16
	v_sub_f32_e32 v20, v15, v13
	v_sub_f32_e32 v15, v15, v20
	v_sub_f32_e32 v19, v13, v19
	v_sub_f32_e32 v13, v15, v13
	v_add_f32_e32 v2, v2, v13
	v_sub_f32_e32 v13, v19, v16
	v_cvt_f32_i32_e32 v4, v4
	v_add_f32_e32 v2, v13, v2
	v_add_f32_e32 v13, v5, v17
	v_add_f32_e32 v2, v20, v2
	v_sub_f32_e32 v5, v13, v5
	v_mul_f32_e32 v2, v18, v2
	v_sub_f32_e32 v5, v17, v5
	v_add_f32_e32 v2, v5, v2
	v_mul_f32_e32 v17, 0x3f317218, v4
	v_add_f32_e32 v5, v13, v2
	v_fma_f32 v18, v4, s62, -v17
	v_mul_f32_e32 v15, v5, v5
	v_fmac_f32_e32 v18, 0xb102e308, v4
	v_sub_f32_e32 v4, v5, v13
	v_fmamk_f32 v16, v15, 0x3e9b6dac, v71
	v_sub_f32_e32 v2, v2, v4
	v_add_f32_e32 v4, v17, v18
	v_fmaak_f32 v16, v15, v16, 0x3f2aaada
	v_sub_f32_e32 v13, v4, v17
	v_ldexp_f32 v17, v5, 1
	v_mul_f32_e32 v5, v5, v15
	v_mul_f32_e32 v5, v5, v16
	v_add_f32_e32 v15, v17, v5
	v_sub_f32_e32 v16, v15, v17
	v_ldexp_f32 v2, v2, 1
	v_sub_f32_e32 v5, v5, v16
	v_add_f32_e32 v2, v2, v5
	v_add_f32_e32 v5, v15, v2
	v_sub_f32_e32 v15, v5, v15
	v_sub_f32_e32 v2, v2, v15
	v_add_f32_e32 v15, v4, v5
	v_sub_f32_e32 v16, v15, v4
	v_sub_f32_e32 v17, v15, v16
	v_sub_f32_e32 v13, v18, v13
	v_sub_f32_e32 v4, v4, v17
	v_sub_f32_e32 v5, v5, v16
	v_add_f32_e32 v4, v5, v4
	v_add_f32_e32 v5, v13, v2
	v_sub_f32_e32 v16, v5, v13
	v_sub_f32_e32 v17, v5, v16
	v_add_f32_e32 v4, v5, v4
	v_sub_f32_e32 v13, v13, v17
	v_sub_f32_e32 v2, v2, v16
	v_add_f32_e32 v5, v15, v4
	v_add_f32_e32 v2, v2, v13
	v_sub_f32_e32 v13, v5, v15
	v_sub_f32_e32 v4, v4, v13
	v_add_f32_e32 v2, v2, v4
	v_add_f32_e32 v2, v5, v2
	v_cmp_neq_f32_e32 vcc, s57, v6
	s_nop 1
	v_cndmask_b32_e32 v2, v112, v2, vcc
	v_cmp_lt_f32_e64 vcc, |v6|, s63
	s_nop 1
	v_cndmask_b32_e32 v2, v2, v6, vcc
	v_add_f32_e32 v2, v14, v2
	v_mul_f32_e64 v2, v2, -v8
	global_store_dword v[0:1], v2, off offset:64
	v_lshl_add_u64 v[0:1], v[66:67], 2, s[34:35]
	global_load_dword v0, v[0:1], off
	s_waitcnt vmcnt(0)
	v_fmamk_f32 v0, v0, 0x3a800000, v65
	v_mul_f32_e32 v1, 0x4b800000, v0
	v_cmp_gt_f32_e32 vcc, s49, v0
	s_nop 1
	v_cndmask_b32_e32 v0, v0, v1, vcc
	v_rsq_f32_e32 v2, v0
	v_lshlrev_b64 v[0:1], 7, v[66:67]
	v_lshl_add_u64 v[0:1], v[68:69], 0, v[0:1]
	v_mul_f32_e32 v4, 0x45800000, v2
	v_cndmask_b32_e32 v2, v2, v4, vcc
	v_fmac_f32_e32 v9, v3, v2
	v_fmac_f32_e32 v10, v7, v2
	v_mul_f32_e32 v2, 0xbfb8aa3b, v9
	v_fma_f32 v4, v9, s48, -v2
	v_rndne_f32_e32 v5, v2
	v_fmac_f32_e32 v4, 0xb2a5705f, v9
	v_sub_f32_e32 v2, v2, v5
	v_add_f32_e32 v3, v11, v10
	v_add_f32_e32 v2, v2, v4
	v_mul_f32_e64 v7, |v3|, s48
	v_cvt_i32_f32_e32 v5, v5
	v_exp_f32_e32 v2, v2
	v_fma_f32 v10, |v3|, s48, -v7
	v_rndne_f32_e32 v11, v7
	v_fma_f32 v4, |v3|, s58, v10
	v_sub_f32_e32 v7, v7, v11
	v_add_f32_e32 v4, v7, v4
	v_cvt_i32_f32_e32 v10, v11
	v_exp_f32_e32 v4, v4
	v_ldexp_f32 v2, v2, v5
	v_cmp_nlt_f32_e32 vcc, s59, v9
	v_max_f32_e32 v6, 0, v3
	v_ldexp_f32 v4, v4, v10
	v_cndmask_b32_e32 v2, 0, v2, vcc
	v_cmp_ngt_f32_e32 vcc, s60, v9
	s_nop 1
	v_cndmask_b32_e32 v2, v112, v2, vcc
	v_add_f32_e32 v5, 1.0, v2
	v_cmp_ngt_f32_e64 vcc, |v3|, s59
	v_div_scale_f32 v7, s[0:1], v5, v5, 1.0
	s_nop 0
	v_cndmask_b32_e32 v4, 0, v4, vcc
	v_cmp_nlt_f32_e64 vcc, |v3|, s60
	v_rcp_f32_e32 v11, v7
	s_nop 0
	v_cndmask_b32_e32 v4, v112, v4, vcc
	v_add_f32_e32 v10, 1.0, v4
	v_add_f32_e32 v12, -1.0, v10
	v_frexp_mant_f32_e32 v13, v10
	v_cvt_f64_f32_e32 v[2:3], v10
	v_sub_f32_e32 v14, v12, v10
	v_frexp_exp_i32_f64_e32 v2, v[2:3]
	v_cmp_gt_f32_e64 s[10:11], s61, v13
	v_fma_f32 v13, -v7, v11, 1.0
	v_div_scale_f32 v9, vcc, 1.0, v5, 1.0
	v_sub_f32_e32 v12, v4, v12
	v_add_f32_e32 v3, 1.0, v14
	v_subbrev_co_u32_e64 v2, s[10:11], 0, v2, s[10:11]
	v_fmac_f32_e32 v11, v13, v11
	v_add_f32_e32 v3, v12, v3
	v_sub_u32_e32 v12, 0, v2
	v_mul_f32_e32 v14, v9, v11
	v_ldexp_f32 v10, v10, v12
	v_fma_f32 v17, -v7, v14, v9
	v_ldexp_f32 v3, v3, v12
	v_add_f32_e32 v12, -1.0, v10
	v_add_f32_e32 v13, 1.0, v10
	v_fmac_f32_e32 v14, v17, v11
	v_add_f32_e32 v15, 1.0, v12
	v_add_f32_e32 v16, -1.0, v13
	v_fma_f32 v7, -v7, v14, v9
	v_sub_f32_e32 v15, v10, v15
	v_sub_f32_e32 v10, v10, v16
	v_div_fmas_f32 v7, v7, v11, v14
	v_add_f32_e32 v15, v3, v15
	v_add_f32_e32 v3, v3, v10
	v_div_fixup_f32 v5, v7, v5, 1.0
	global_store_dword v[0:1], v5, off
	v_add_f32_e32 v5, v13, v3
	v_rcp_f32_e32 v7, v5
	v_add_f32_e32 v9, v12, v15
	v_sub_f32_e32 v11, v13, v5
	v_add_f32_e32 v3, v3, v11
	v_mul_f32_e32 v11, v9, v7
	v_sub_f32_e32 v10, v12, v9
	v_mul_f32_e32 v12, v5, v11
	v_fma_f32 v13, v11, v5, -v12
	v_fmac_f32_e32 v13, v11, v3
	v_add_f32_e32 v14, v12, v13
	v_add_f32_e32 v10, v15, v10
	v_sub_f32_e32 v15, v9, v14
	v_sub_f32_e32 v9, v9, v15
	v_sub_f32_e32 v12, v14, v12
	v_sub_f32_e32 v9, v9, v14
	v_add_f32_e32 v9, v10, v9
	v_sub_f32_e32 v10, v12, v13
	v_add_f32_e32 v9, v10, v9
	v_add_f32_e32 v10, v15, v9
	v_mul_f32_e32 v12, v7, v10
	v_mul_f32_e32 v13, v5, v12
	v_fma_f32 v5, v12, v5, -v13
	v_fmac_f32_e32 v5, v12, v3
	v_sub_f32_e32 v3, v15, v10
	v_add_f32_e32 v3, v9, v3
	v_add_f32_e32 v9, v13, v5
	v_sub_f32_e32 v14, v10, v9
	v_sub_f32_e32 v10, v10, v14
	v_sub_f32_e32 v13, v9, v13
	v_sub_f32_e32 v9, v10, v9
	v_add_f32_e32 v3, v3, v9
	v_sub_f32_e32 v5, v13, v5
	v_add_f32_e32 v3, v5, v3
	v_cvt_f32_i32_e32 v2, v2
	v_add_f32_e32 v3, v14, v3
	v_add_f32_e32 v5, v11, v12
	v_mul_f32_e32 v3, v7, v3
	v_sub_f32_e32 v7, v5, v11
	v_sub_f32_e32 v7, v12, v7
	v_add_f32_e32 v3, v7, v3
	v_mul_f32_e32 v11, 0x3f317218, v2
	v_add_f32_e32 v7, v5, v3
	v_fma_f32 v12, v2, s62, -v11
	v_mul_f32_e32 v9, v7, v7
	v_fmac_f32_e32 v12, 0xb102e308, v2
	v_sub_f32_e32 v2, v7, v5
	v_fmamk_f32 v10, v9, 0x3e9b6dac, v71
	v_sub_f32_e32 v2, v3, v2
	v_add_f32_e32 v3, v11, v12
	v_fmaak_f32 v10, v9, v10, 0x3f2aaada
	v_sub_f32_e32 v5, v3, v11
	v_ldexp_f32 v11, v7, 1
	v_mul_f32_e32 v7, v7, v9
	v_mul_f32_e32 v7, v7, v10
	v_add_f32_e32 v9, v11, v7
	v_sub_f32_e32 v10, v9, v11
	v_ldexp_f32 v2, v2, 1
	v_sub_f32_e32 v7, v7, v10
	v_add_f32_e32 v2, v2, v7
	v_add_f32_e32 v7, v9, v2
	v_sub_f32_e32 v9, v7, v9
	v_sub_f32_e32 v2, v2, v9
	v_add_f32_e32 v9, v3, v7
	v_sub_f32_e32 v10, v9, v3
	v_sub_f32_e32 v11, v9, v10
	v_sub_f32_e32 v5, v12, v5
	v_sub_f32_e32 v3, v3, v11
	v_sub_f32_e32 v7, v7, v10
	v_add_f32_e32 v3, v7, v3
	v_add_f32_e32 v7, v5, v2
	v_sub_f32_e32 v10, v7, v5
	v_sub_f32_e32 v11, v7, v10
	v_sub_f32_e32 v5, v5, v11
	v_sub_f32_e32 v2, v2, v10
	v_add_f32_e32 v3, v7, v3
	v_add_f32_e32 v2, v2, v5
	v_add_f32_e32 v5, v9, v3
	v_sub_f32_e32 v7, v5, v9
	v_sub_f32_e32 v3, v3, v7
	v_add_f32_e32 v2, v2, v3
	v_add_f32_e32 v2, v5, v2
	v_cmp_neq_f32_e32 vcc, s57, v4
	s_nop 1
	v_cndmask_b32_e32 v2, v112, v2, vcc
	v_cmp_lt_f32_e64 vcc, |v4|, s63
	s_nop 1
	v_cndmask_b32_e32 v2, v2, v4, vcc
	v_add_f32_e32 v2, v6, v2
	v_mul_f32_e64 v2, v2, -v8
	global_store_dword v[0:1], v2, off offset:64
	s_branch .LBB0_796
